# GEMM1 epilogue store tails: six staged rows per feature half read from LDS together before their row stores (was read, lgkmcnt(0), store per row)
# speedup vs baseline: 1.0014x; 1.0014x over previous
;     __device__ __forceinline__ bf16_t* PROJ() const { return (bf16_t*)(ws + OFF_PROJ); }
; #define LAS __attribute__((address_space(3)))
; __device__ __forceinline__ void phase_gemm1(const Params& p, int layer, LAS unsigned char* lds) {
;     ...
;                     bf16_t* dbase = p.PROJ() + col0;
;                     const size_t dld = INW;
; #pragma unroll
;                     for (int i = 0; i < 8; i++) {
;                         const int c = lane2 + 64 * i, row = c >> 3, ch = c & 7;
;                         const u32x4 w = *(const LAS u32x4*)(lds + wid * 9216 + row * LROW + ch * 16);
;                         const int tk2 = mt * 256 + (row >> 5) * 128 + wc * 32 + (row & 31);
;                         *(u32x4*)(dbase + (size_t)tk2 * dld + ch * 8) = w;
;                     }
.LBB0_285:
	v_and_b32_e32 v0, 7, v141
	v_and_b32_e32 v75, 63, v141
	v_lshlrev_b32_e32 v70, 4, v0
	v_lshlrev_b32_e32 v0, 3, v0
	v_add_u32_e32 v72, s92, v70
	s_mov_b64 s[10:11], -1
	s_and_b64 vcc, exec, s[76:77]
	v_lshlrev_b32_e32 v66, 1, v0
	v_lshrrev_b32_e32 v71, 3, v75
	s_cbranch_vccz .LBB0_287
	s_lshl_b64 s[10:11], s[66:67], 1
	s_add_u32 s10, s60, s10
	s_addc_u32 s11, s61, s11
	v_mov_b32_e32 v67, v1
	v_lshl_add_u64 v[68:69], s[10:11], 0, v[66:67]
	v_lshrrev_b32_e32 v67, 3, v75
	s_movk_i32 s10, 0x90
	v_mad_u32_u24 v0, v67, s10, v72
	ds_read_b128 v[224:227], v0
	ds_read_b128 v[228:231], v0 offset:1152
	ds_read_b128 v[232:235], v0 offset:2304
	ds_read_b128 v[236:239], v0 offset:3456
	ds_read_b128 v[240:243], v0 offset:4608
	ds_read_b128 v[244:247], v0 offset:5760
	v_or_b32_e32 v73, s24, v67
	v_mad_i64_i32 v[80:81], s[10:11], v73, s80, v[68:69]
	v_or_b32_e32 v74, 8, v67
	s_waitcnt lgkmcnt(5)
	global_store_dwordx4 v[80:81], v[224:227], off
	s_nop 0
	v_or_b32_e32 v80, s24, v74
	v_mad_i64_i32 v[80:81], s[10:11], v80, s80, v[68:69]
	v_or_b32_e32 v73, 24, v73
	s_waitcnt lgkmcnt(4)
	global_store_dwordx4 v[80:81], v[228:231], off
	s_nop 0
	v_or_b32_e32 v76, 16, v67
	v_or_b32_e32 v77, s24, v76
	v_mad_i64_i32 v[82:83], s[10:11], v77, s80, v[68:69]
	s_waitcnt lgkmcnt(3)
	global_store_dwordx4 v[82:83], v[232:235], off
	s_nop 0
	v_mad_i64_i32 v[82:83], s[10:11], v73, s80, v[68:69]
	s_or_b32 s10, s56, s93
	s_nop 0
	v_or_b32_e32 v73, s10, v67
	s_waitcnt lgkmcnt(2)
	global_store_dwordx4 v[82:83], v[236:239], off
	s_nop 0
	v_mad_i64_i32 v[82:83], s[10:11], v73, s80, v[68:69]
	v_or_b32_e32 v73, s93, v74
	v_or_b32_e32 v73, s56, v73
	s_waitcnt lgkmcnt(1)
	global_store_dwordx4 v[82:83], v[240:243], off
	s_nop 0
	v_mad_i64_i32 v[82:83], s[10:11], v73, s80, v[68:69]
	v_add_u32_e32 v77, 0x1b00, v0
	s_mov_b64 s[10:11], 0
	s_waitcnt lgkmcnt(0)
	global_store_dwordx4 v[82:83], v[244:247], off

;     __device__ __forceinline__ bf16_t* PROJ() const { return (bf16_t*)(ws + OFF_PROJ); }
; #define LAS __attribute__((address_space(3)))
; __device__ __forceinline__ void phase_gemm1(const Params& p, int layer, LAS unsigned char* lds) {
;     ...
;                     bf16_t* dbase = p.PROJ() + col0;
;                     const size_t dld = INW;
; #pragma unroll
;                     for (int i = 0; i < 8; i++) {
;                         const int c = lane2 + 64 * i, row = c >> 3, ch = c & 7;
;                         const u32x4 w = *(const LAS u32x4*)(lds + wid * 9216 + row * LROW + ch * 16);
;                         const int tk2 = mt * 256 + (row >> 5) * 128 + wc * 32 + (row & 31);
;                         *(u32x4*)(dbase + (size_t)tk2 * dld + ch * 8) = w;
;                     }
.LBB0_368:
	s_and_b64 vcc, exec, s[0:1]
	s_mov_b64 s[0:1], -1
	s_cbranch_vccnz .LBB0_371
	s_lshl_b64 s[0:1], s[66:67], 1
	s_add_u32 s0, s60, s0
	s_addc_u32 s1, s61, s1
	v_mov_b32_e32 v67, v1
	v_lshl_add_u64 v[2:3], s[0:1], 0, v[66:67]
	s_movk_i32 s0, 0x90
	v_mad_u32_u24 v12, v71, s0, v72
	ds_read_b128 v[224:227], v12
	ds_read_b128 v[228:231], v12 offset:1152
	ds_read_b128 v[232:235], v12 offset:2304
	ds_read_b128 v[236:239], v12 offset:3456
	ds_read_b128 v[240:243], v12 offset:4608
	ds_read_b128 v[244:247], v12 offset:5760
	v_or_b32_e32 v13, s24, v71
	v_mad_i64_i32 v[8:9], s[0:1], v13, s80, v[2:3]
	v_or_b32_e32 v14, 8, v71
	s_waitcnt lgkmcnt(5)
	global_store_dwordx4 v[8:9], v[224:227], off
	s_nop 0
	v_or_b32_e32 v8, s24, v14
	v_mad_i64_i32 v[8:9], s[0:1], v8, s80, v[2:3]
	s_waitcnt lgkmcnt(4)
	global_store_dwordx4 v[8:9], v[228:231], off
	s_nop 0
	v_or_b32_e32 v4, 16, v71
	v_or_b32_e32 v5, s24, v4
	v_mad_i64_i32 v[10:11], s[0:1], v5, s80, v[2:3]
	s_waitcnt lgkmcnt(3)
	global_store_dwordx4 v[10:11], v[232:235], off
	s_nop 0
	v_or_b32_e32 v5, 24, v13
	v_mad_i64_i32 v[10:11], s[0:1], v5, s80, v[2:3]
	s_or_b32 s0, s56, s93
	s_waitcnt lgkmcnt(2)
	global_store_dwordx4 v[10:11], v[236:239], off
	s_nop 0
	v_or_b32_e32 v5, s0, v71
	v_mad_i64_i32 v[10:11], s[0:1], v5, s80, v[2:3]
	v_or_b32_e32 v5, s93, v14
	s_waitcnt lgkmcnt(1)
	global_store_dwordx4 v[10:11], v[240:243], off
	s_nop 0
	v_or_b32_e32 v5, s56, v5
	v_mad_i64_i32 v[10:11], s[0:1], v5, s80, v[2:3]
	v_add_u32_e32 v5, 0x1b00, v12
	s_waitcnt lgkmcnt(0)
	global_store_dwordx4 v[10:11], v[244:247], off
	s_cbranch_execz .LBB0_372
